# v106 with a 4096-tile layer-1 w_in slice on the retention workgroups (8 tiles per wave)
# baseline (speedup 1.0000x reference)
.Lmy_a_m6:
	s_add_i32 s76, s76, 0xffffff80
	s_movk_i32 s3, 64
	s_movk_i32 s96, 0x200
	s_lshl_b32 s2, s76, 3
	s_add_i32 s2, s2, s30
	s_movk_i32 s101, 0x1000
	s_branch .Lmy_a_it

.Lmy_a_it:
	s_cmp_ge_i32 s2, s101
	s_waitcnt lgkmcnt(0)
	s_barrier
	s_cbranch_scc1 .LBB0_88
	s_load_dwordx2 s[8:9], s[6:7], 0x38
	v_readlane_b32 s12, v255, 8
	s_load_dwordx2 s[10:11], s[6:7], 0xc8
	s_nop 0
	s_load_dwordx2 s[6:7], s[6:7], 0xa8
	v_readlane_b32 s13, v255, 9
	s_mul_i32 s0, s12, 0xd080000
	s_mov_b32 s13, s89
	s_waitcnt lgkmcnt(0)
	s_add_u32 s42, s8, s0
	s_addc_u32 s43, s9, 0
	s_lshl_b64 s[8:9], s[12:13], 26
	s_add_u32 s44, s10, s8
	s_addc_u32 s45, s11, s9
	s_lshl_b64 s[8:9], s[12:13], 22
	s_add_u32 s46, s6, s8
	s_addc_u32 s47, s7, s9
	s_lshl_b64 s[6:7], s[12:13], 21
	s_add_u32 s6, s4, s6
	s_mov_b32 s0, s12
	s_addc_u32 s7, s5, s7
	v_writelane_b32 v255, s0, 8
	s_lshl_b64 s[8:9], s[12:13], 25
	s_add_u32 s8, s4, s8
	v_writelane_b32 v255, s1, 9
	s_mul_i32 s0, s30, 0x4400
	s_addc_u32 s9, s5, s9
	s_add_i32 s10, s0, 0
	v_lshrrev_b32_e32 v11, 4, v16
	v_mov_b32_e32 v2, s10
	s_movk_i32 s11, 0x110
	v_and_b32_e32 v3, 7, v8
	v_mad_u32_u24 v31, v11, s11, v2
	v_lshrrev_b32_e32 v42, 3, v16
	s_movk_i32 s11, 0x880
	v_lshlrev_b32_e32 v5, 2, v3
	v_mad_u32_u24 v4, v3, s11, v2
	v_xor_b32_e32 v6, v5, v42
	v_lshl_add_u32 v43, v6, 2, v4
	v_bitop3_b32 v6, v42, v5, 8 bitop3:0x36
	v_lshl_add_u32 v45, v6, 2, v4
	v_bitop3_b32 v6, v42, v5, 16 bitop3:0x36
	v_lshl_add_u32 v47, v6, 2, v4
	v_bitop3_b32 v6, v42, v5, 24 bitop3:0x36
	v_lshl_add_u32 v49, v6, 2, v4
	v_bitop3_b32 v6, v42, v5, 32 bitop3:0x36
	v_lshlrev_b32_e32 v12, 3, v16
	v_lshl_add_u32 v51, v6, 2, v4
	v_bitop3_b32 v6, v42, v5, 40 bitop3:0x36
	v_and_b32_e32 v12, 56, v12
	v_lshlrev_b32_e32 v194, 4, v3
	v_lshl_add_u32 v53, v6, 2, v4
	v_bitop3_b32 v6, v42, v5, 48 bitop3:0x36
	v_mul_u32_u24_e32 v14, 0x84, v12
	v_lshlrev_b32_e32 v12, 1, v12
	v_mov_b32_e32 v13, v195
	v_lshlrev_b32_e32 v15, 2, v42
	v_lshl_add_u32 v55, v6, 2, v4
	v_lshrrev_b32_e32 v6, 5, v16
	v_lshl_add_u64 v[12:13], s[4:5], 0, v[12:13]
	v_add3_u32 v58, s10, v14, v15
	v_lshl_add_u64 v[14:15], s[4:5], 0, v[194:195]
	s_mov_b64 s[4:5], 0x100000
	v_lshl_add_u64 v[2:3], s[6:7], 0, v[194:195]
	s_mov_b64 s[6:7], 0xab00000
	v_bitop3_b32 v5, v42, v5, 56 bitop3:0x36
	v_and_b32_e32 v17, 31, v8
	v_lshl_add_u64 v[14:15], v[14:15], 0, s[4:5]
	s_mul_i32 s4, s30, 0xfff2f800
	v_readlane_b32 s5, v254, 24
	v_mul_u32_u24_e32 v21, 0x84, v6
	v_and_b32_e32 v7, 15, v8
	v_lshl_add_u64 v[2:3], v[2:3], 0, s[6:7]
	v_or_b32_e32 v44, 8, v42
	v_or_b32_e32 v46, 16, v42
	v_or_b32_e32 v48, 24, v42
	v_lshl_add_u32 v57, v5, 2, v4
	v_lshl_add_u64 v[4:5], s[8:9], 0, v[194:195]
	s_mov_b64 s[6:7], 0x6b00000
	v_lshlrev_b32_e32 v19, 2, v17
	s_add_i32 s4, s4, s5
	v_or_b32_e32 v21, s0, v21
	s_mul_i32 s30, s30, 0xd0800
	s_mul_i32 s0, s76, 0x684000
	v_lshlrev_b32_e32 v9, 2, v7
	v_lshlrev_b32_e32 v34, 4, v7
	v_lshl_add_u64 v[4:5], v[4:5], 0, s[6:7]
	v_add_u32_e32 v10, s10, v19
	s_mov_b64 s[6:7], 0xaf00000
	v_lshlrev_b32_e32 v16, 12, v42
	v_lshlrev_b32_e32 v18, 12, v44
	v_lshlrev_b32_e32 v20, 12, v46
	v_lshlrev_b32_e32 v22, 12, v48
	v_cmp_lt_u32_e64 s[38:39], 7, v7
	v_mov_b32_e32 v7, s4
	s_movk_i32 s4, 0xcbe0
	v_add3_u32 v61, v21, v19, 0
	s_add_i32 s0, s0, s30
	v_mul_u32_u24_e32 v19, 0x3420, v6
	v_xor_b32_e32 v35, 16, v34
	v_xor_b32_e32 v36, 32, v34
	v_xor_b32_e32 v37, 48, v34
	v_xor_b32_e32 v38, 64, v34
	v_xor_b32_e32 v39, 0x50, v34
	v_xor_b32_e32 v40, 0x60, v34
	v_xor_b32_e32 v41, 0x70, v34
	v_or_b32_e32 v50, 32, v42
	v_or_b32_e32 v52, 40, v42
	v_or_b32_e32 v54, 48, v42
	v_or_b32_e32 v56, 56, v42
	v_or_b32_e32 v8, 0x1c00, v17
	v_lshl_add_u64 v[12:13], v[12:13], 0, s[6:7]
	v_subrev_u32_e32 v59, 32, v9
	v_mad_i32_i24 v60, v6, s4, v7
	v_mov_b32_e32 v7, v6
	v_add3_u32 v62, s0, v19, v17
	s_mov_b32 s8, 0
	v_lshlrev_b32_e32 v16, 1, v16
	v_lshlrev_b32_e32 v18, 1, v18
	v_lshlrev_b32_e32 v20, 1, v20
	v_lshlrev_b32_e32 v22, 1, v22
	s_cmp_eq_u32 s100, 0
	s_cbranch_scc0 .Lmy_a_k0
	s_cmpk_lg_i32 s3, 0x100
	s_cbranch_scc1 .Lmy_a_k0
	v_readlane_b32 s4, v255, 8
	s_nop 3
	s_cmp_eq_u32 s4, 1
	s_cbranch_scc0 .Lmy_a_k0
	s_add_i32 s2, s2, s96
	s_add_i32 s8, s8, 1
	s_mul_i32 s0, s3, 0x684000
	v_add_u32_e32 v62, s0, v62
	s_branch .LBB0_40
